# ps1 + packed bias adds split in the prompt-diff tail loop + loop back-edge scalar block moved in front of the iteration-end barrier
# speedup vs baseline: 1.0008x; 1.0008x over previous
.LBB0_463:
	s_mov_b32 s8, s60
	s_mov_b32 s9, s16
	s_mov_b32 s10, s59
	ds_read_b128 v[4:7], v219 offset:1024
	v_lshl_add_u32 v207, s11, 14, v214
	v_add_f32_e32 v2, v100, v101
	v_add_f32_e32 v2, v102, v2
	v_add_f32_e32 v2, v103, v2
	v_add_f32_e32 v2, v104, v2
	v_add_f32_e32 v2, v105, v2
	v_cvt_pk_bf16_f32 v160, v100, v101
	v_cvt_pk_bf16_f32 v161, v102, v103
	s_waitcnt lgkmcnt(1)
	v_mfma_f32_32x32x16_bf16 v[132:147], v[192:195], v[116:119], 0
	v_mfma_f32_32x32x16_bf16 v[116:131], v[184:187], v[116:119], 0
	v_add_f32_e32 v2, v106, v2
	v_add_f32_e32 v2, v107, v2
	v_add_f32_e32 v2, v108, v2
	v_add_f32_e32 v2, v109, v2
	v_cvt_pk_bf16_f32 v162, v104, v105
	v_cvt_pk_bf16_f32 v163, v106, v107
	ds_read_b128 v[10:13], v219 offset:2048
	ds_read_b64_tr_b16 v[14:15], v207 offset:24576
	ds_read_b64_tr_b16 v[16:17], v207 offset:25088
	v_add_f32_e32 v2, v110, v2
	v_add_f32_e32 v2, v111, v2
	v_add_f32_e32 v2, v112, v2
	v_add_f32_e32 v2, v113, v2
	v_cvt_pk_bf16_f32 v156, v108, v109
	v_cvt_pk_bf16_f32 v157, v110, v111
	s_waitcnt lgkmcnt(3)
	v_mfma_f32_32x32x16_bf16 v[132:147], v[188:191], v[4:7], v[132:147]
	v_mfma_f32_32x32x16_bf16 v[116:131], v[180:183], v[4:7], v[116:131]
	v_add_f32_e32 v2, v114, v2
	v_add_f32_e32 v2, v115, v2
	v_add_f32_e32 v2, v84, v2
	v_add_f32_e32 v2, v85, v2
	v_cvt_pk_bf16_f32 v158, v112, v113
	v_cvt_pk_bf16_f32 v159, v114, v115
	ds_read_b128 v[4:7], v219 offset:3072
	ds_read_b64_tr_b16 v[100:101], v207 offset:28672
	ds_read_b64_tr_b16 v[102:103], v207 offset:29184
	v_add_f32_e32 v2, v86, v2
	v_add_f32_e32 v2, v87, v2
	v_add_f32_e32 v2, v88, v2
	v_add_f32_e32 v2, v89, v2
	v_cvt_pk_bf16_f32 v152, v84, v85
	v_cvt_pk_bf16_f32 v153, v86, v87
	s_waitcnt lgkmcnt(5)
	v_mfma_f32_32x32x16_bf16 v[132:147], v[176:179], v[10:13], v[132:147]
	v_mfma_f32_32x32x16_bf16 v[116:131], v[172:175], v[10:13], v[116:131]
	v_add_f32_e32 v2, v90, v2
	v_add_f32_e32 v2, v91, v2
	v_add_f32_e32 v2, v92, v2
	v_add_f32_e32 v2, v93, v2
	v_cvt_pk_bf16_f32 v154, v88, v89
	v_cvt_pk_bf16_f32 v155, v90, v91
	ds_read_b64_tr_b16 v[84:85], v207 offset:25600
	ds_read_b64_tr_b16 v[86:87], v207 offset:26112
	v_add_f32_e32 v2, v94, v2
	v_add_f32_e32 v2, v95, v2
	v_add_f32_e32 v2, v96, v2
	v_add_f32_e32 v2, v97, v2
	v_cvt_pk_bf16_f32 v148, v92, v93
	v_cvt_pk_bf16_f32 v149, v94, v95
	s_waitcnt lgkmcnt(4)
	v_mfma_f32_32x32x16_bf16 v[132:147], v[168:171], v[4:7], v[132:147]
	v_mfma_f32_32x32x16_bf16 v[116:131], v[164:167], v[4:7], v[116:131]
	v_add_f32_e32 v2, v98, v2
	v_add_f32_e32 v2, v99, v2
	v_cvt_pk_bf16_f32 v150, v96, v97
	v_cvt_pk_bf16_f32 v151, v98, v99
	v_add_f32_e32 v2, v225, v2
	ds_read_b64_tr_b16 v[4:5], v207 offset:29696
	ds_read_b64_tr_b16 v[6:7], v207 offset:30208
	v_mfma_f32_32x32x16_bf16 v[68:83], v[160:163], v[14:17], v[68:83]
	v_exp_f32_e32 v132, v132
	v_exp_f32_e32 v133, v133
	ds_read_b64_tr_b16 v[14:15], v207 offset:26624
	ds_read_b64_tr_b16 v[16:17], v207 offset:27136
	s_waitcnt lgkmcnt(6)
	v_mfma_f32_32x32x16_bf16 v[52:67], v[160:163], v[100:103], v[52:67]
	v_exp_f32_e32 v134, v134
	v_exp_f32_e32 v135, v135
	s_add_u32 s98, s6, s28
	s_addc_u32 s99, s7, s29
	v_lshl_add_u64 v[254:255], v[204:205], 0, s[98:99]
	s_lshl_b32 s100, s59, 13
	s_add_i32 s100, s100, s49
	s_mov_b32 m0, s100
	s_nop 0
	global_load_lds_dwordx4 v[254:255], off
	ds_read_b64_tr_b16 v[88:89], v207 offset:30720
	ds_read_b64_tr_b16 v[90:91], v207 offset:31232
	s_waitcnt lgkmcnt(6)
	v_mfma_f32_32x32x16_bf16 v[68:83], v[156:159], v[84:87], v[68:83]
	v_exp_f32_e32 v136, v136
	v_exp_f32_e32 v137, v137
	ds_read_b64_tr_b16 v[84:85], v207 offset:27648
	ds_read_b64_tr_b16 v[86:87], v207 offset:28160
	s_waitcnt lgkmcnt(6)
	v_mfma_f32_32x32x16_bf16 v[52:67], v[156:159], v[4:7], v[52:67]
	v_exp_f32_e32 v138, v138
	v_exp_f32_e32 v139, v139
	ds_read_b64_tr_b16 v[4:5], v207 offset:31744
	ds_read_b64_tr_b16 v[6:7], v207 offset:32256
	s_waitcnt lgkmcnt(6)
	v_mfma_f32_32x32x16_bf16 v[68:83], v[152:155], v[14:17], v[68:83]
	v_exp_f32_e32 v140, v140
	v_exp_f32_e32 v141, v141
	s_add_u32 s98, s6, s30
	s_addc_u32 s99, s7, s31
	v_lshl_add_u64 v[254:255], v[8:9], 0, s[98:99]
	s_lshl_b32 s100, s60, 14
	s_add_i32 s100, s100, s58
	s_mov_b32 m0, s100
	s_nop 0
	global_load_lds_dwordx4 v[254:255], off
	ds_read_b64_tr_b16 v[14:15], v207 offset:32768
	ds_read_b64_tr_b16 v[16:17], v207 offset:33280
	s_waitcnt lgkmcnt(6)
	v_mfma_f32_32x32x16_bf16 v[52:67], v[152:155], v[88:91], v[52:67]
	v_exp_f32_e32 v142, v142
	v_exp_f32_e32 v143, v143
	ds_read_b64_tr_b16 v[88:89], v207 offset:36864
	ds_read_b64_tr_b16 v[90:91], v207 offset:37376
	s_waitcnt lgkmcnt(6)
	v_mfma_f32_32x32x16_bf16 v[68:83], v[148:151], v[84:87], v[68:83]
	v_exp_f32_e32 v144, v144
	v_exp_f32_e32 v145, v145
	ds_read_b64_tr_b16 v[84:85], v207 offset:33792
	ds_read_b64_tr_b16 v[86:87], v207 offset:34304
	s_waitcnt lgkmcnt(6)
	v_mfma_f32_32x32x16_bf16 v[52:67], v[148:151], v[4:7], v[52:67]
	v_exp_f32_e32 v146, v146
	v_exp_f32_e32 v147, v147
	ds_read_b64_tr_b16 v[92:93], v207 offset:37888
	ds_read_b64_tr_b16 v[94:95], v207 offset:38400
	s_lshl_b32 s11, s60, 13
	v_add_u32_e32 v4, s11, v222
	ds_read_b128 v[96:99], v4
	ds_read_b128 v[164:167], v4 offset:512
	s_waitcnt lgkmcnt(8)
	v_mfma_f32_32x32x16_bf16 v[36:51], v[160:163], v[14:17], v[36:51]
	v_exp_f32_e32 v116, v116
	v_exp_f32_e32 v117, v117
	ds_read_b64_tr_b16 v[14:15], v207 offset:34816
	ds_read_b64_tr_b16 v[16:17], v207 offset:35328
	ds_read_b128 v[168:171], v4 offset:2048
	ds_read_b128 v[172:175], v4 offset:2560
	s_waitcnt lgkmcnt(10)
	v_mfma_f32_32x32x16_bf16 v[20:35], v[160:163], v[88:91], v[20:35]
	v_exp_f32_e32 v118, v118
	v_exp_f32_e32 v119, v119
	ds_read_b64_tr_b16 v[88:89], v207 offset:38912
	ds_read_b64_tr_b16 v[90:91], v207 offset:39424
	ds_read_b128 v[176:179], v4 offset:4096
	ds_read_b128 v[180:183], v4 offset:4608
	s_waitcnt lgkmcnt(12)
	v_mfma_f32_32x32x16_bf16 v[36:51], v[156:159], v[84:87], v[36:51]
	v_exp_f32_e32 v120, v120
	v_exp_f32_e32 v121, v121
	ds_read_b64_tr_b16 v[84:85], v207 offset:35840
	ds_read_b64_tr_b16 v[86:87], v207 offset:36352
	ds_read_b128 v[184:187], v4 offset:6144
	ds_read_b128 v[4:7], v4 offset:6656
	s_waitcnt lgkmcnt(14)
	v_mfma_f32_32x32x16_bf16 v[20:35], v[156:159], v[92:95], v[20:35]
	v_exp_f32_e32 v122, v122
	v_exp_f32_e32 v123, v123
	ds_read_b64_tr_b16 v[92:93], v207 offset:39936
	ds_read_b64_tr_b16 v[94:95], v207 offset:40448
	s_waitcnt lgkmcnt(12)
	v_mfma_f32_32x32x16_bf16 v[36:51], v[152:155], v[14:17], v[36:51]
	v_exp_f32_e32 v124, v124
	v_exp_f32_e32 v125, v125
	ds_read_b128 v[14:17], v219
	s_waitcnt lgkmcnt(9)
	v_mfma_f32_32x32x16_bf16 v[20:35], v[152:155], v[88:91], v[20:35]
	v_exp_f32_e32 v126, v126
	v_exp_f32_e32 v127, v127
	s_add_u32 s98, s6, s34
	s_addc_u32 s99, s7, s35
	v_lshl_add_u64 v[254:255], v[8:9], 0, s[98:99]
	s_lshl_b32 s100, s60, 14
	s_add_i32 s100, s100, s58
	s_addk_i32 s100, 0x2000
	s_mov_b32 m0, s100
	s_nop 0
	global_load_lds_dwordx4 v[254:255], off
	s_waitcnt lgkmcnt(5)
	v_mfma_f32_32x32x16_bf16 v[36:51], v[148:151], v[84:87], v[36:51]
	v_exp_f32_e32 v128, v128
	v_exp_f32_e32 v129, v129
	s_waitcnt lgkmcnt(1)
	v_mfma_f32_32x32x16_bf16 v[20:35], v[148:151], v[92:95], v[20:35]
	v_exp_f32_e32 v130, v130
	v_exp_f32_e32 v131, v131
	s_waitcnt vmcnt(3) lgkmcnt(0)
	s_barrier
	s_add_i32 s16, s60, 1
	s_cmp_lg_u32 s60, 2
	s_cselect_b32 s59, s16, 0
	ds_read_b128 v[188:191], v219 offset:1024
	v_lshl_add_u32 v207, s10, 14, v214
	s_waitcnt lgkmcnt(1)
	v_mfma_f32_32x32x16_bf16 v[100:115], v[96:99], v[14:17], 0
	v_add_f32_e32 v84, v132, v133
	v_add_f32_e32 v84, v134, v84
	v_add_f32_e32 v84, v135, v84
	v_add_f32_e32 v84, v136, v84
	v_add_f32_e32 v84, v137, v84
	v_cvt_pk_bf16_f32 v160, v132, v133
	v_cvt_pk_bf16_f32 v161, v134, v135
	s_nop 0
	v_add_f32_e32 v84, v138, v84
	v_add_f32_e32 v84, v139, v84
	v_add_f32_e32 v84, v140, v84
	v_add_f32_e32 v148, v141, v84
	v_mfma_f32_32x32x16_bf16 v[84:99], v[164:167], v[14:17], 0
	v_cvt_pk_bf16_f32 v162, v136, v137
	v_cvt_pk_bf16_f32 v163, v138, v139
	ds_read_b128 v[14:17], v219 offset:2048
	ds_read_b64_tr_b16 v[132:133], v207 offset:24576
	ds_read_b64_tr_b16 v[134:135], v207 offset:25088
	s_waitcnt lgkmcnt(3)
	v_mfma_f32_32x32x16_bf16 v[100:115], v[168:171], v[188:191], v[100:115]
	v_add_f32_e32 v136, v142, v148
	v_add_f32_e32 v136, v143, v136
	v_add_f32_e32 v136, v144, v136
	v_add_f32_e32 v136, v145, v136
	v_cvt_pk_bf16_f32 v156, v140, v141
	v_cvt_pk_bf16_f32 v157, v142, v143
	v_mfma_f32_32x32x16_bf16 v[84:99], v[172:175], v[188:191], v[84:99]
	v_add_f32_e32 v136, v146, v136
	v_add_f32_e32 v136, v147, v136
	v_add_f32_e32 v136, v116, v136
	v_add_f32_e32 v148, v117, v136
	v_cvt_pk_bf16_f32 v158, v144, v145
	v_cvt_pk_bf16_f32 v159, v146, v147
	ds_read_b128 v[136:139], v219 offset:3072
	ds_read_b64_tr_b16 v[140:141], v207 offset:28672
	ds_read_b64_tr_b16 v[142:143], v207 offset:29184
	s_waitcnt lgkmcnt(5)
	v_mfma_f32_32x32x16_bf16 v[100:115], v[176:179], v[14:17], v[100:115]
	v_add_f32_e32 v144, v118, v148
	v_add_f32_e32 v144, v119, v144
	v_add_f32_e32 v144, v120, v144
	v_add_f32_e32 v144, v121, v144
	v_cvt_pk_bf16_f32 v152, v116, v117
	v_cvt_pk_bf16_f32 v153, v118, v119
	v_mfma_f32_32x32x16_bf16 v[84:99], v[180:183], v[14:17], v[84:99]
	v_add_f32_e32 v14, v122, v144
	v_add_f32_e32 v14, v123, v14
	v_add_f32_e32 v14, v124, v14
	v_add_f32_e32 v116, v125, v14
	v_cvt_pk_bf16_f32 v154, v120, v121
	v_cvt_pk_bf16_f32 v155, v122, v123
	ds_read_b64_tr_b16 v[14:15], v207 offset:25600
	ds_read_b64_tr_b16 v[16:17], v207 offset:26112
	s_waitcnt lgkmcnt(4)
	v_mfma_f32_32x32x16_bf16 v[100:115], v[184:187], v[136:139], v[100:115]
	v_add_f32_e32 v116, v126, v116
	v_add_f32_e32 v116, v127, v116
	v_add_f32_e32 v116, v128, v116
	v_add_f32_e32 v116, v129, v116
	v_cvt_pk_bf16_f32 v148, v124, v125
	v_cvt_pk_bf16_f32 v149, v126, v127
	v_mfma_f32_32x32x16_bf16 v[84:99], v[4:7], v[136:139], v[84:99]
	v_add_f32_e32 v4, v130, v116
	v_add_f32_e32 v4, v131, v4
	v_cvt_pk_bf16_f32 v150, v128, v129
	v_cvt_pk_bf16_f32 v151, v130, v131
	v_add_f32_e32 v225, v2, v4
	ds_read_b64_tr_b16 v[4:5], v207 offset:29696
	ds_read_b64_tr_b16 v[6:7], v207 offset:30208
	v_mfma_f32_32x32x16_bf16 v[68:83], v[160:163], v[132:135], v[68:83]
	v_exp_f32_e32 v100, v100
	v_exp_f32_e32 v101, v101
	ds_read_b64_tr_b16 v[10:11], v207 offset:26624
	ds_read_b64_tr_b16 v[12:13], v207 offset:27136
	s_waitcnt lgkmcnt(6)
; #define TWAIT_BAR(N) asm volatile("s_waitcnt vmcnt(" #N ") lgkmcnt(0)\n\ts_barrier" ::: "memory")
; #define RESC() do { if constexpr (!NOMAX) if (resc) { asm volatile("s_waitcnt lgkmcnt(0)" ::: "memory"); \
;         _Pragma("unroll") for (int d_ = 0; d_ < 2; ++d_) _Pragma("unroll") for (int r = 0; r < 16; ++r) o[d_][r] *= wsf[crow(r, hi)]; } } while (0)
; #define ROT() do { sl_prev = sl_cur; sl_cur = sl_next; sl_next = (sl_next == 2 * SLOTB) ? 0 : sl_next + SLOTB; } while (0)
; #define RESC() do { if constexpr (!NOMAX) if (resc) { asm volatile("s_waitcnt lgkmcnt(0)" ::: "memory"); \
;         _Pragma("unroll") for (int d_ = 0; d_ < 4; ++d_) _Pragma("unroll") for (int r = 0; r < 16; ++r) o[d_][r] *= wsf[crow(r, hi)]; } } while (0)
; #define ROT() do { sl_prev = sl_cur; sl_cur = sl_next; sl_next = (sl_next == 2) ? 0 : sl_next + 1; } while (0)
; #define RESC() do { if (resc) { asm volatile("s_waitcnt lgkmcnt(0)" ::: "memory"); \
;         _Pragma("unroll") for (int d_ = 0; d_ < 4; ++d_) _Pragma("unroll") for (int r = 0; r < 16; ++r) o[d_][r] *= wsf[crow(r, hi)]; } } while (0)
; template <bool NOMAX>
; __device__ __forceinline__ void diff_unit(const AttnCtx& C, int u, LAS unsigned char* lds) {
;     ...
;         STEP(pB0, pB1, pA0, pA1, kk, true, true, true, false);     TWAIT_BAR(3); RESC(); ROT();
;         STEP(pA0, pA1, pB0, pB1, kk + 1, true, true, true, false); TWAIT_BAR(3); RESC(); ROT();
	v_mfma_f32_32x32x16_bf16 v[52:67], v[160:163], v[140:143], v[52:67]
	v_exp_f32_e32 v102, v102
	v_exp_f32_e32 v103, v103
	s_add_u32 s98, s6, s36
	s_addc_u32 s99, s7, s37
	v_lshl_add_u64 v[254:255], v[204:205], 0, s[98:99]
	s_lshl_b32 s100, s60, 13
	s_add_i32 s100, s100, s49
	s_mov_b32 m0, s100
	s_nop 0
	global_load_lds_dwordx4 v[254:255], off
	ds_read_b64_tr_b16 v[116:117], v207 offset:30720
	ds_read_b64_tr_b16 v[118:119], v207 offset:31232
	s_waitcnt lgkmcnt(6)
	v_mfma_f32_32x32x16_bf16 v[68:83], v[156:159], v[14:17], v[68:83]
	v_exp_f32_e32 v104, v104
	v_exp_f32_e32 v105, v105
	ds_read_b64_tr_b16 v[14:15], v207 offset:27648
	ds_read_b64_tr_b16 v[16:17], v207 offset:28160
	s_waitcnt lgkmcnt(6)
	v_mfma_f32_32x32x16_bf16 v[52:67], v[156:159], v[4:7], v[52:67]
	v_exp_f32_e32 v106, v106
	v_exp_f32_e32 v107, v107
	ds_read_b64_tr_b16 v[4:5], v207 offset:31744
	ds_read_b64_tr_b16 v[6:7], v207 offset:32256
	s_waitcnt lgkmcnt(6)
	v_mfma_f32_32x32x16_bf16 v[68:83], v[152:155], v[10:13], v[68:83]
	v_exp_f32_e32 v108, v108
	v_exp_f32_e32 v109, v109
	s_add_u32 s98, s6, s38
	s_addc_u32 s99, s7, s39
	v_lshl_add_u64 v[254:255], v[8:9], 0, s[98:99]
	s_lshl_b32 s100, s59, 14
	s_add_i32 s100, s100, s58
	s_mov_b32 m0, s100
	s_nop 0
	global_load_lds_dwordx4 v[254:255], off
	ds_read_b64_tr_b16 v[10:11], v207 offset:32768
	ds_read_b64_tr_b16 v[12:13], v207 offset:33280
	s_waitcnt lgkmcnt(6)
	v_mfma_f32_32x32x16_bf16 v[52:67], v[152:155], v[116:119], v[52:67]
	v_exp_f32_e32 v110, v110
	v_exp_f32_e32 v111, v111
	ds_read_b64_tr_b16 v[116:117], v207 offset:36864
	ds_read_b64_tr_b16 v[118:119], v207 offset:37376
	s_waitcnt lgkmcnt(6)
	v_mfma_f32_32x32x16_bf16 v[68:83], v[148:151], v[14:17], v[68:83]
	v_exp_f32_e32 v112, v112
	v_exp_f32_e32 v113, v113
	ds_read_b64_tr_b16 v[14:15], v207 offset:33792
	ds_read_b64_tr_b16 v[16:17], v207 offset:34304
	s_waitcnt lgkmcnt(6)
	v_mfma_f32_32x32x16_bf16 v[52:67], v[148:151], v[4:7], v[52:67]
	v_exp_f32_e32 v114, v114
	v_exp_f32_e32 v115, v115
	ds_read_b64_tr_b16 v[4:5], v207 offset:37888
	ds_read_b64_tr_b16 v[6:7], v207 offset:38400
	v_lshl_add_u32 v2, s59, 13, v222
	ds_read_b128 v[192:195], v2
	ds_read_b128 v[184:187], v2 offset:512
	s_waitcnt lgkmcnt(8)
	v_mfma_f32_32x32x16_bf16 v[36:51], v[160:163], v[10:13], v[36:51]
	v_exp_f32_e32 v84, v84
	v_exp_f32_e32 v85, v85
	ds_read_b64_tr_b16 v[10:11], v207 offset:34816
	ds_read_b64_tr_b16 v[12:13], v207 offset:35328
	ds_read_b128 v[188:191], v2 offset:2048
	ds_read_b128 v[180:183], v2 offset:2560
	s_waitcnt lgkmcnt(10)
	v_mfma_f32_32x32x16_bf16 v[20:35], v[160:163], v[116:119], v[20:35]
	v_exp_f32_e32 v86, v86
	v_exp_f32_e32 v87, v87
	ds_read_b64_tr_b16 v[120:121], v207 offset:38912
	ds_read_b64_tr_b16 v[122:123], v207 offset:39424
	ds_read_b128 v[176:179], v2 offset:4096
	ds_read_b128 v[172:175], v2 offset:4608
	s_waitcnt lgkmcnt(12)
	v_mfma_f32_32x32x16_bf16 v[36:51], v[156:159], v[14:17], v[36:51]
	v_exp_f32_e32 v88, v88
	v_exp_f32_e32 v89, v89
	ds_read_b64_tr_b16 v[14:15], v207 offset:35840
	ds_read_b64_tr_b16 v[16:17], v207 offset:36352
	ds_read_b128 v[168:171], v2 offset:6144
	ds_read_b128 v[164:167], v2 offset:6656
	s_waitcnt lgkmcnt(14)
	v_mfma_f32_32x32x16_bf16 v[20:35], v[156:159], v[4:7], v[20:35]
	v_exp_f32_e32 v90, v90
	v_exp_f32_e32 v91, v91
	ds_read_b64_tr_b16 v[4:5], v207 offset:39936
	ds_read_b64_tr_b16 v[6:7], v207 offset:40448
	s_waitcnt lgkmcnt(12)
	v_mfma_f32_32x32x16_bf16 v[36:51], v[152:155], v[10:13], v[36:51]
	v_exp_f32_e32 v92, v92
	v_exp_f32_e32 v93, v93
	ds_read_b128 v[116:119], v219
	s_waitcnt lgkmcnt(9)
	v_mfma_f32_32x32x16_bf16 v[20:35], v[152:155], v[120:123], v[20:35]
	v_exp_f32_e32 v94, v94
	v_exp_f32_e32 v95, v95
	s_add_u32 s98, s6, s40
	s_addc_u32 s99, s7, s41
	v_lshl_add_u64 v[254:255], v[8:9], 0, s[98:99]
	s_lshl_b32 s100, s59, 14
	s_add_i32 s100, s100, s58
	s_addk_i32 s100, 0x2000
	s_mov_b32 m0, s100
	s_nop 0
	global_load_lds_dwordx4 v[254:255], off
	s_waitcnt lgkmcnt(5)
	v_mfma_f32_32x32x16_bf16 v[36:51], v[148:151], v[14:17], v[36:51]
	v_exp_f32_e32 v96, v96
	v_exp_f32_e32 v97, v97
	s_waitcnt lgkmcnt(1)
	v_mfma_f32_32x32x16_bf16 v[20:35], v[148:151], v[4:7], v[20:35]
	v_exp_f32_e32 v98, v98
	v_exp_f32_e32 v99, v99
	s_add_i32 s10, s59, 1
	s_cmp_lg_u32 s59, 2
	s_cselect_b32 s60, s10, 0
	s_add_i32 s16, s9, 2
	s_add_u32 s6, s6, 0x20000
	v_cmp_ge_u32_e32 vcc, s16, v226
	s_addc_u32 s7, s7, 0
	s_mov_b32 s11, s8
	s_waitcnt vmcnt(3) lgkmcnt(0)
	s_barrier
	s_cbranch_vccz .LBB0_463
	s_add_i32 s16, s9, -5
	s_branch .LBB0_467

.LBB0_473:
	v_lshl_add_u64 v[206:207], v[16:17], 0, s[46:47]
	s_lshl_b32 s63, s60, 14
	v_lshl_add_u64 v[84:85], v[206:207], 0, s[42:43]
	s_add_i32 s6, s63, s58
	s_mov_b32 s7, m0
	s_mov_b32 m0, s6
	s_nop 0
	global_load_lds_dwordx4 v[84:85], off
	s_mov_b32 m0, s7
	s_add_i32 s11, s10, -1
	v_lshl_add_u64 v[84:85], v[206:207], 0, s[44:45]
	s_addk_i32 s6, 0x2000
	s_mov_b32 s7, m0
	s_mov_b32 m0, s6
	s_nop 0
	global_load_lds_dwordx4 v[84:85], off
	s_mov_b32 m0, s7
	v_cmp_lt_i32_e32 vcc, s11, v236
	s_cbranch_vccnz .LBB0_479
	v_cmp_gt_i32_e32 vcc, s11, v223
	v_mov_b32_e32 v84, 0xff800000
	s_and_b64 vcc, exec, vcc
	v_mov_b32_e32 v85, 0xff800000
	v_mov_b32_e32 v86, 0xff800000
	v_mov_b32_e32 v87, 0xff800000
	v_mov_b32_e32 v88, 0xff800000
	v_mov_b32_e32 v89, 0xff800000
	v_mov_b32_e32 v90, 0xff800000
	v_mov_b32_e32 v91, 0xff800000
	v_mov_b32_e32 v92, 0xff800000
	v_mov_b32_e32 v93, 0xff800000
	v_mov_b32_e32 v94, 0xff800000
	v_mov_b32_e32 v95, 0xff800000
	v_mov_b32_e32 v96, 0xff800000
	v_mov_b32_e32 v97, 0xff800000
	v_mov_b32_e32 v98, 0xff800000
	v_mov_b32_e32 v99, 0xff800000
	v_mov_b32_e32 v100, 0xff800000
	v_mov_b32_e32 v101, 0xff800000
	v_mov_b32_e32 v102, 0xff800000
	v_mov_b32_e32 v103, 0xff800000
	v_mov_b32_e32 v104, 0xff800000
	v_mov_b32_e32 v105, 0xff800000
	v_mov_b32_e32 v106, 0xff800000
	v_mov_b32_e32 v107, 0xff800000
	v_mov_b32_e32 v108, 0xff800000
	v_mov_b32_e32 v109, 0xff800000
	v_mov_b32_e32 v110, 0xff800000
	v_mov_b32_e32 v111, 0xff800000
	v_mov_b32_e32 v112, 0xff800000
	v_mov_b32_e32 v113, 0xff800000
	v_mov_b32_e32 v114, 0xff800000
	v_mov_b32_e32 v115, 0xff800000
	s_cbranch_vccnz .LBB0_478
	v_add_u32_e32 v84, s16, v237
	v_cmp_gt_i32_e32 vcc, s53, v84
	s_cbranch_vccnz .LBB0_477
	v_add_u32_e32 v84, s62, v238
	v_add_u32_e32 v87, 1, v84
	v_add_u32_e32 v89, 2, v84
	v_add_u32_e32 v91, 3, v84
	v_med3_i32 v85, v84, s51, 63
	v_med3_i32 v86, v84, s52, 31
	v_med3_i32 v88, v87, s51, 63
	v_med3_i32 v87, v87, s52, 31
	v_med3_i32 v90, v89, s51, 63
	v_med3_i32 v89, v89, s52, 31
	v_med3_i32 v92, v91, s51, 63
	v_med3_i32 v91, v91, s52, 31
	v_lshl_add_u32 v85, v85, 2, v235
	v_lshl_add_u32 v86, v86, 2, v235
	v_lshl_add_u32 v88, v88, 2, v235
	v_lshl_add_u32 v87, v87, 2, v235
	v_lshl_add_u32 v89, v89, 2, v235
	v_lshl_add_u32 v91, v91, 2, v235
	v_lshl_add_u32 v90, v90, 2, v235
	v_lshl_add_u32 v92, v92, 2, v235
	ds_read_b32 v85, v85 offset:512
	ds_read_b32 v100, v86 offset:640
	ds_read_b32 v86, v88 offset:512
	ds_read_b32 v101, v87 offset:640
	ds_read_b32 v88, v90 offset:512
	ds_read_b32 v102, v89 offset:640
	ds_read_b32 v87, v92 offset:512
	ds_read_b32 v103, v91 offset:640
	v_add_u32_e32 v89, 8, v84
	v_add_u32_e32 v91, 9, v84
	v_add_u32_e32 v93, 10, v84
	v_add_u32_e32 v95, 11, v84
	v_med3_i32 v90, v89, s51, 63
	v_med3_i32 v89, v89, s52, 31
	v_med3_i32 v92, v91, s51, 63
	v_med3_i32 v91, v91, s52, 31
	v_med3_i32 v94, v93, s51, 63
	v_med3_i32 v93, v93, s52, 31
	v_med3_i32 v96, v95, s51, 63
	v_med3_i32 v95, v95, s52, 31
	v_lshl_add_u32 v90, v90, 2, v235
	v_lshl_add_u32 v89, v89, 2, v235
	v_lshl_add_u32 v92, v92, 2, v235
	v_lshl_add_u32 v91, v91, 2, v235
	v_lshl_add_u32 v93, v93, 2, v235
	v_lshl_add_u32 v95, v95, 2, v235
	v_lshl_add_u32 v94, v94, 2, v235
	v_lshl_add_u32 v96, v96, 2, v235
	ds_read_b32 v90, v90 offset:512
	ds_read_b32 v104, v89 offset:640
	ds_read_b32 v89, v92 offset:512
	ds_read_b32 v105, v91 offset:640
	ds_read_b32 v92, v94 offset:512
	ds_read_b32 v106, v93 offset:640
	ds_read_b32 v91, v96 offset:512
	ds_read_b32 v107, v95 offset:640
	v_add_u32_e32 v93, 16, v84
	v_add_u32_e32 v95, 17, v84
	v_add_u32_e32 v97, 18, v84
	v_add_u32_e32 v99, 19, v84
	v_med3_i32 v94, v93, s51, 63
	v_med3_i32 v93, v93, s52, 31
	v_med3_i32 v96, v95, s51, 63
	v_med3_i32 v95, v95, s52, 31
	v_med3_i32 v98, v97, s51, 63
	v_med3_i32 v97, v97, s52, 31
	v_med3_i32 v108, v99, s51, 63
	v_med3_i32 v99, v99, s52, 31
	v_lshl_add_u32 v94, v94, 2, v235
	v_lshl_add_u32 v93, v93, 2, v235
	v_lshl_add_u32 v96, v96, 2, v235
	v_lshl_add_u32 v95, v95, 2, v235
	v_lshl_add_u32 v97, v97, 2, v235
	v_lshl_add_u32 v108, v108, 2, v235
	v_lshl_add_u32 v99, v99, 2, v235
	v_lshl_add_u32 v98, v98, 2, v235
	ds_read_b32 v94, v94 offset:512
	ds_read_b32 v109, v93 offset:640
	ds_read_b32 v93, v96 offset:512
	ds_read_b32 v110, v95 offset:640
	ds_read_b32 v96, v98 offset:512
	ds_read_b32 v111, v97 offset:640
	ds_read_b32 v95, v108 offset:512
	ds_read_b32 v108, v99 offset:640
	v_add_u32_e32 v97, 24, v84
	v_add_u32_e32 v99, 25, v84
	v_add_u32_e32 v113, 26, v84
	v_add_u32_e32 v84, 27, v84
	v_med3_i32 v98, v97, s51, 63
	v_med3_i32 v97, v97, s52, 31
	v_med3_i32 v112, v99, s51, 63
	v_med3_i32 v99, v99, s52, 31
	v_med3_i32 v114, v113, s51, 63
	v_med3_i32 v113, v113, s52, 31
	v_med3_i32 v115, v84, s51, 63
	v_lshl_add_u32 v98, v98, 2, v235
	v_lshl_add_u32 v97, v97, 2, v235
	v_lshl_add_u32 v112, v112, 2, v235
	v_lshl_add_u32 v99, v99, 2, v235
	v_lshl_add_u32 v114, v114, 2, v235
	v_lshl_add_u32 v113, v113, 2, v235
	v_med3_i32 v164, v84, s52, 31
	v_lshl_add_u32 v115, v115, 2, v235
	s_waitcnt lgkmcnt(14)
	v_sub_f32_e32 v84, v85, v213
	v_sub_f32_e32 v85, v86, v213
	v_sub_f32_e32 v86, v88, v213
	v_sub_f32_e32 v88, v90, v213
	s_waitcnt lgkmcnt(11)
	v_sub_f32_e32 v90, v92, v213
	s_waitcnt lgkmcnt(7)
	v_sub_f32_e32 v92, v94, v213
	s_waitcnt lgkmcnt(3)
	v_sub_f32_e32 v94, v96, v213
	v_lshl_add_u32 v96, v164, 2, v235
	ds_read_b32 v98, v98 offset:512
	ds_read_b32 v164, v97 offset:640
	ds_read_b32 v97, v112 offset:512
	ds_read_b32 v112, v99 offset:640
	ds_read_b32 v114, v114 offset:512
	ds_read_b32 v99, v115 offset:512
	ds_read_b32 v115, v96 offset:640
	ds_read_b32 v113, v113 offset:640
	v_sub_f32_e32 v87, v87, v213
	v_sub_f32_e32 v89, v89, v213
	v_sub_f32_e32 v91, v91, v213
	v_sub_f32_e32 v93, v93, v213
	s_waitcnt lgkmcnt(9)
	v_sub_f32_e32 v95, v95, v213
	s_waitcnt lgkmcnt(5)
	v_sub_f32_e32 v97, v97, v213
	v_sub_f32_e32 v96, v98, v213
	s_waitcnt lgkmcnt(2)
	v_sub_f32_e32 v99, v99, v213
	v_sub_f32_e32 v98, v114, v213
	v_add_f32_e32 v146, v146, v98
	v_add_f32_e32 v147, v147, v99
	v_add_f32_e32 v144, v144, v96
	v_add_f32_e32 v145, v145, v97
	v_add_f32_e32 v142, v142, v94
	v_add_f32_e32 v143, v143, v95
	v_add_f32_e32 v140, v140, v92
	v_add_f32_e32 v141, v141, v93
	v_add_f32_e32 v138, v138, v90
	v_add_f32_e32 v139, v139, v91
	v_add_f32_e32 v136, v136, v88
	v_add_f32_e32 v137, v137, v89
	v_add_f32_e32 v134, v134, v86
	v_add_f32_e32 v135, v135, v87
	v_add_f32_e32 v132, v132, v84
	v_add_f32_e32 v133, v133, v85
	v_sub_f32_e32 v84, v100, v213
	v_sub_f32_e32 v85, v101, v213
	v_sub_f32_e32 v87, v103, v213
	v_sub_f32_e32 v86, v102, v213
	v_sub_f32_e32 v89, v105, v213
	v_sub_f32_e32 v88, v104, v213
	v_sub_f32_e32 v91, v107, v213
	v_sub_f32_e32 v90, v106, v213
	v_sub_f32_e32 v93, v110, v213
	v_sub_f32_e32 v92, v109, v213
	v_sub_f32_e32 v95, v108, v213
	v_sub_f32_e32 v94, v111, v213
	v_sub_f32_e32 v97, v112, v213
	v_sub_f32_e32 v96, v164, v213
	s_waitcnt lgkmcnt(1)
	v_sub_f32_e32 v99, v115, v213
	s_waitcnt lgkmcnt(0)
	v_sub_f32_e32 v98, v113, v213
	v_add_f32_e32 v130, v130, v98
	v_add_f32_e32 v131, v131, v99
	v_add_f32_e32 v128, v128, v96
	v_add_f32_e32 v129, v129, v97
	v_add_f32_e32 v126, v126, v94
	v_add_f32_e32 v127, v127, v95
	v_add_f32_e32 v124, v124, v92
	v_add_f32_e32 v125, v125, v93
	v_add_f32_e32 v122, v122, v90
	v_add_f32_e32 v123, v123, v91
	v_add_f32_e32 v120, v120, v88
	v_add_f32_e32 v121, v121, v89
	v_add_f32_e32 v118, v118, v86
	v_add_f32_e32 v119, v119, v87
	v_add_f32_e32 v116, v116, v84
	v_add_f32_e32 v117, v117, v85

.LBB0_491:
	v_cmp_lt_i32_e32 vcc, s10, v236
	s_cbranch_vccnz .LBB0_497
	v_cmp_ge_i32_e32 vcc, s11, v223
	v_mov_b32_e32 v116, 0xff800000
	s_and_b64 vcc, exec, vcc
	v_mov_b32_e32 v117, 0xff800000
	v_mov_b32_e32 v118, 0xff800000
	v_mov_b32_e32 v119, 0xff800000
	v_mov_b32_e32 v120, 0xff800000
	v_mov_b32_e32 v121, 0xff800000
	v_mov_b32_e32 v122, 0xff800000
	v_mov_b32_e32 v123, 0xff800000
	v_mov_b32_e32 v125, 0xff800000
	v_mov_b32_e32 v126, 0xff800000
	v_mov_b32_e32 v127, 0xff800000
	v_mov_b32_e32 v128, 0xff800000
	v_mov_b32_e32 v129, 0xff800000
	v_mov_b32_e32 v130, 0xff800000
	v_mov_b32_e32 v131, 0xff800000
	v_mov_b32_e32 v132, 0xff800000
	v_mov_b32_e32 v133, 0xff800000
	v_mov_b32_e32 v134, 0xff800000
	v_mov_b32_e32 v135, 0xff800000
	v_mov_b32_e32 v136, 0xff800000
	v_mov_b32_e32 v137, 0xff800000
	v_mov_b32_e32 v138, 0xff800000
	v_mov_b32_e32 v139, 0xff800000
	v_mov_b32_e32 v140, 0xff800000
	v_mov_b32_e32 v141, 0xff800000
	v_mov_b32_e32 v142, 0xff800000
	v_mov_b32_e32 v143, 0xff800000
	v_mov_b32_e32 v144, 0xff800000
	v_mov_b32_e32 v145, 0xff800000
	v_mov_b32_e32 v146, 0xff800000
	v_mov_b32_e32 v147, 0xff800000
	v_mov_b32_e32 v206, 0xff800000
	s_cbranch_vccnz .LBB0_496
	v_add_u32_e32 v116, s62, v237
	v_add_u32_e32 v116, 64, v116
	v_cmp_ge_i32_e32 vcc, s61, v116
	s_cbranch_vccnz .LBB0_495
	v_add_u32_e32 v116, s62, v238
	v_add_u32_e32 v117, 64, v116
	v_add_u32_e32 v119, 0x41, v116
	v_add_u32_e32 v121, 0x42, v116
	v_add_u32_e32 v123, 0x43, v116
	v_med3_i32 v118, v117, s51, 63
	v_med3_i32 v117, v117, s52, 31
	v_med3_i32 v120, v119, s51, 63
	v_med3_i32 v119, v119, s52, 31
	v_med3_i32 v122, v121, s51, 63
	v_med3_i32 v121, v121, s52, 31
	v_med3_i32 v125, v123, s51, 63
	v_med3_i32 v123, v123, s52, 31
	v_lshl_add_u32 v118, v118, 2, v235
	v_lshl_add_u32 v117, v117, 2, v235
	v_lshl_add_u32 v120, v120, 2, v235
	v_lshl_add_u32 v119, v119, 2, v235
	v_lshl_add_u32 v121, v121, 2, v235
	v_lshl_add_u32 v125, v125, 2, v235
	v_lshl_add_u32 v123, v123, 2, v235
	v_lshl_add_u32 v122, v122, 2, v235
	ds_read_b32 v118, v118 offset:512
	ds_read_b32 v134, v117 offset:640
	ds_read_b32 v117, v120 offset:512
	ds_read_b32 v135, v119 offset:640
	ds_read_b32 v120, v122 offset:512
	ds_read_b32 v136, v121 offset:640
	ds_read_b32 v119, v125 offset:512
	ds_read_b32 v125, v123 offset:640
	v_add_u32_e32 v121, 0x48, v116
	v_add_u32_e32 v123, 0x49, v116
	v_add_u32_e32 v127, 0x4a, v116
	v_add_u32_e32 v129, 0x4b, v116
	v_med3_i32 v122, v121, s51, 63
	v_med3_i32 v121, v121, s52, 31
	v_med3_i32 v126, v123, s51, 63
	v_med3_i32 v123, v123, s52, 31
	v_med3_i32 v128, v127, s51, 63
	v_med3_i32 v127, v127, s52, 31
	v_med3_i32 v130, v129, s51, 63
	v_med3_i32 v129, v129, s52, 31
	v_lshl_add_u32 v122, v122, 2, v235
	v_lshl_add_u32 v121, v121, 2, v235
	v_lshl_add_u32 v126, v126, 2, v235
	v_lshl_add_u32 v123, v123, 2, v235
	v_lshl_add_u32 v127, v127, 2, v235
	v_lshl_add_u32 v129, v129, 2, v235
	v_lshl_add_u32 v128, v128, 2, v235
	v_lshl_add_u32 v130, v130, 2, v235
	ds_read_b32 v122, v122 offset:512
	ds_read_b32 v137, v121 offset:640
	ds_read_b32 v121, v126 offset:512
	ds_read_b32 v138, v123 offset:640
	ds_read_b32 v126, v128 offset:512
	ds_read_b32 v139, v127 offset:640
	ds_read_b32 v123, v130 offset:512
	ds_read_b32 v140, v129 offset:640
	v_add_u32_e32 v127, 0x50, v116
	v_add_u32_e32 v129, 0x51, v116
	v_add_u32_e32 v131, 0x52, v116
	v_add_u32_e32 v133, 0x53, v116
	v_med3_i32 v128, v127, s51, 63
	v_med3_i32 v127, v127, s52, 31
	v_med3_i32 v130, v129, s51, 63
	v_med3_i32 v129, v129, s52, 31
	v_med3_i32 v132, v131, s51, 63
	v_med3_i32 v131, v131, s52, 31
	v_med3_i32 v141, v133, s51, 63
	v_med3_i32 v133, v133, s52, 31
	v_lshl_add_u32 v128, v128, 2, v235
	v_lshl_add_u32 v127, v127, 2, v235
	v_lshl_add_u32 v130, v130, 2, v235
	v_lshl_add_u32 v129, v129, 2, v235
	v_lshl_add_u32 v131, v131, 2, v235
	v_lshl_add_u32 v141, v141, 2, v235
	v_lshl_add_u32 v133, v133, 2, v235
	v_lshl_add_u32 v132, v132, 2, v235
	ds_read_b32 v128, v128 offset:512
	ds_read_b32 v142, v127 offset:640
	ds_read_b32 v127, v130 offset:512
	ds_read_b32 v143, v129 offset:640
	ds_read_b32 v130, v132 offset:512
	ds_read_b32 v144, v131 offset:640
	ds_read_b32 v129, v141 offset:512
	ds_read_b32 v141, v133 offset:640
	v_add_u32_e32 v131, 0x58, v116
	v_add_u32_e32 v133, 0x59, v116
	v_add_u32_e32 v146, 0x5a, v116
	v_add_u32_e32 v116, 0x5b, v116
	v_med3_i32 v132, v131, s51, 63
	v_med3_i32 v131, v131, s52, 31
	v_med3_i32 v145, v133, s51, 63
	v_med3_i32 v133, v133, s52, 31
	v_med3_i32 v147, v146, s51, 63
	v_med3_i32 v146, v146, s52, 31
	v_med3_i32 v206, v116, s51, 63
	v_lshl_add_u32 v132, v132, 2, v235
	v_lshl_add_u32 v131, v131, 2, v235
	v_lshl_add_u32 v145, v145, 2, v235
	v_lshl_add_u32 v133, v133, 2, v235
	v_lshl_add_u32 v147, v147, 2, v235
	v_lshl_add_u32 v146, v146, 2, v235
	v_med3_i32 v207, v116, s52, 31
	v_lshl_add_u32 v206, v206, 2, v235
	s_waitcnt lgkmcnt(14)
	v_sub_f32_e32 v116, v118, v213
	v_sub_f32_e32 v118, v120, v213
	v_sub_f32_e32 v120, v122, v213
	s_waitcnt lgkmcnt(11)
	v_sub_f32_e32 v122, v126, v213
	s_waitcnt lgkmcnt(7)
	v_sub_f32_e32 v126, v128, v213
	s_waitcnt lgkmcnt(3)
	v_sub_f32_e32 v128, v130, v213
	v_lshl_add_u32 v130, v207, 2, v235
	ds_read_b32 v132, v132 offset:512
	ds_read_b32 v207, v131 offset:640
	ds_read_b32 v131, v145 offset:512
	ds_read_b32 v145, v133 offset:640
	ds_read_b32 v147, v147 offset:512
	ds_read_b32 v133, v206 offset:512
	ds_read_b32 v206, v130 offset:640
	ds_read_b32 v146, v146 offset:640
	v_sub_f32_e32 v117, v117, v213
	v_sub_f32_e32 v119, v119, v213
	v_sub_f32_e32 v121, v121, v213
	v_sub_f32_e32 v123, v123, v213
	v_sub_f32_e32 v127, v127, v213
	s_waitcnt lgkmcnt(9)
	v_sub_f32_e32 v129, v129, v213
	s_waitcnt lgkmcnt(5)
	v_sub_f32_e32 v131, v131, v213
	v_sub_f32_e32 v130, v132, v213
	s_waitcnt lgkmcnt(2)
	v_sub_f32_e32 v133, v133, v213
	v_sub_f32_e32 v132, v147, v213
	v_add_f32_e32 v114, v114, v132
	v_add_f32_e32 v115, v115, v133
	v_add_f32_e32 v112, v112, v130
	v_add_f32_e32 v113, v113, v131
	v_add_f32_e32 v110, v110, v128
	v_add_f32_e32 v111, v111, v129
	v_add_f32_e32 v108, v108, v126
	v_add_f32_e32 v109, v109, v127
	v_add_f32_e32 v106, v106, v122
	v_add_f32_e32 v107, v107, v123
	v_add_f32_e32 v104, v104, v120
	v_add_f32_e32 v105, v105, v121
	v_add_f32_e32 v102, v102, v118
	v_add_f32_e32 v103, v103, v119
	v_add_f32_e32 v100, v100, v116
	v_add_f32_e32 v101, v101, v117
	v_sub_f32_e32 v117, v135, v213
	v_sub_f32_e32 v116, v134, v213
	v_sub_f32_e32 v119, v125, v213
	v_sub_f32_e32 v118, v136, v213
	v_sub_f32_e32 v121, v138, v213
	v_sub_f32_e32 v120, v137, v213
	v_sub_f32_e32 v123, v140, v213
	v_sub_f32_e32 v122, v139, v213
	v_sub_f32_e32 v127, v143, v213
	v_sub_f32_e32 v126, v142, v213
	v_sub_f32_e32 v129, v141, v213
	v_sub_f32_e32 v128, v144, v213
	v_sub_f32_e32 v131, v145, v213
	v_sub_f32_e32 v130, v207, v213
	s_waitcnt lgkmcnt(1)
	v_sub_f32_e32 v133, v206, v213
	s_waitcnt lgkmcnt(0)
	v_sub_f32_e32 v132, v146, v213
	v_add_f32_e32 v98, v98, v132
	v_add_f32_e32 v99, v99, v133
	v_add_f32_e32 v96, v96, v130
	v_add_f32_e32 v97, v97, v131
	v_add_f32_e32 v94, v94, v128
	v_add_f32_e32 v95, v95, v129
	v_add_f32_e32 v92, v92, v126
	v_add_f32_e32 v93, v93, v127
	v_add_f32_e32 v90, v90, v122
	v_add_f32_e32 v91, v91, v123
	v_add_f32_e32 v88, v88, v120
	v_add_f32_e32 v89, v89, v121
	v_add_f32_e32 v86, v86, v118
	v_add_f32_e32 v87, v87, v119
	v_add_f32_e32 v84, v84, v116
	v_add_f32_e32 v85, v85, v117
